# attention rewritten: K/V tiles via LDS-DMA into 4-slot LDS ring, 1 barrier per tile, fixed-offset softmax (score upper bound), f32 accumulate
# speedup vs baseline: 1.0164x; 1.0076x over previous
; __device__ __forceinline__ void attn_unit(int b, int qb, int kvh, const bf16_t* __restrict__ QP, const bf16_t* __restrict__ KP, const bf16_t* __restrict__ VT, const float* sink, bf16_t* MIX, unsigned char* ldsb, int tid, int wave, int lane) {
;     const int fr = lane & 15, fq = lane >> 4, hq = kvh * 4 + (wave >> 1), q0 = qb * 64 + (wave & 1) * 32;
;     bf16x8 qf[2][2];
; #pragma unroll
;     for (int qt = 0; qt < 2; ++qt)
; #pragma unroll
;         for (int ks = 0; ks < 2; ++ks) qf[qt][ks] = *(const bf16x8*)(QP + ((size_t)(b * 4096 + q0 + qt * 16 + fr) * 8 + hq) * 64 + ks * 32 + fq * 8);
;     const bf16_t* Kb = KP + (size_t)(b * 2 + kvh) * KPL * 64; const bf16_t* Vb = VT + (size_t)(b * 2 + kvh) * 64 * KPL;
;     float mrun[2], lrun[2]; f32x4 o[4][2];
;     const float sk = sink[hq] * LOG2E;
; #pragma unroll
;     for (int qt = 0; qt < 2; ++qt) { mrun[qt] = sk; lrun[qt] = fq == 0 ? 1.0f : 0.0f;
; #pragma unroll
;         for (int dt = 0; dt < 4; ++dt) o[dt][qt] = (f32x4){0.f, 0.f, 0.f, 0.f}; }
;     const int first = qb == 0 ? 2 : (qb == 1 ? 1 : 0), lastw = (65 - qb) < 4 ? (65 - qb) : 4, nW = lastw - first + 1, nT = nW + 4;
;     ...
;     bf16_t* const lb = (bf16_t*)ldsb; const int lr = tid >> 3, lc = tid & 7;
;     u32x4 kreg = *(const u32x4*)(Kb + (size_t)(ATT_KS0(0) + lr) * 64 + lc * 8), vreg = *(const u32x4*)(Vb + (size_t)lr * KPL + ATT_KS0(0) + lc * 8);
.Lat_scan_done:
	s_barrier
	s_lshr_b32 s13, s2, 1
	s_and_b32 s13, s13, 63
	s_and_b32 s0, s2, 1
	s_lshr_b32 s1, s2, 7
	s_sub_u32 s21, 2, s13
	s_max_i32 s21, s21, 0
	s_sub_u32 s4, 0x41, s13
	s_min_i32 s4, s4, 4
	s_sub_u32 s24, s4, s21
	s_add_u32 s24, s24, 1
	s_add_u32 s25, s24, 4
	s_lshl_b32 s26, s25, 2
	s_lshl_b32 s34, s12, 10
	s_lshl_b32 s4, s1, 1
	s_add_u32 s4, s4, s0
	s_mul_i32 s4, s4, 0x88000
	s_add_u32 s8, s88, s4
	s_addc_u32 s9, s89, 0
	s_add_u32 s10, s8, 0x17d00000
	s_addc_u32 s11, s9, 0
	s_add_u32 s8, s8, 0x17400000
	s_addc_u32 s9, s9, 0
	s_lshr_b32 s4, s12, 1
	s_lshl_b32 s5, s0, 2
	s_add_u32 s4, s4, s5
	s_lshl_b32 s5, s1, 12
	s_lshl_b32 s6, s13, 6
	s_add_u32 s5, s5, s6
	s_and_b32 s6, s12, 1
	s_lshl_b32 s7, s6, 5
	s_add_u32 s5, s5, s7
	s_lshl_b32 s7, s4, 7
	s_lshl_b32 s44, s5, 10
	s_add_u32 s44, s44, s7
	s_add_u32 s50, s88, s44
	s_addc_u32 s51, s89, 0
	s_add_u32 s50, s50, 0x10d00000
	s_addc_u32 s51, s51, 0
	s_lshl_b32 s44, s5, 11
	s_add_u32 s44, s44, s7
	s_add_u32 s52, s88, s44
	s_addc_u32 s53, s89, 0
	s_add_u32 s52, s52, 0x1a600000
	s_addc_u32 s53, s53, 0
	s_lshl_b32 s44, s4, 2
	s_load_dword s45, s[62:63], s44
	v_and_b32_e32 v80, 15, v1
	v_lshrrev_b32_e32 v81, 4, v1
	v_lshrrev_b32_e32 v82, 1, v80
	v_lshlrev_b32_e32 v83, 7, v80
	v_xor_b32_e32 v84, v81, v82
	v_lshl_add_u32 v2, v84, 4, v83
	v_xor_b32_e32 v3, 64, v2
	v_lshrrev_b32_e32 v84, 1, v81
	v_xor_b32_e32 v84, v84, v82
	v_lshl_add_u32 v84, v84, 4, v83
	v_and_b32_e32 v85, 1, v81
	v_lshl_add_u32 v4, v85, 3, v84
	v_xor_b32_e32 v5, 32, v4
	v_xor_b32_e32 v6, 64, v4
	v_xor_b32_e32 v7, 0x60, v4
	v_lshrrev_b32_e32 v84, 3, v1
	v_and_b32_e32 v85, 7, v1
	v_lshrrev_b32_e32 v86, 1, v84
	s_lshl_b32 s44, s6, 2
	v_or_b32_e32 v86, s44, v86
	v_xor_b32_e32 v85, v85, v86
	v_lshlrev_b32_e32 v85, 4, v85
	s_lshl_b32 s44, s12, 3
	v_add_u32_e32 v84, s44, v84
	v_lshl_add_u32 v14, v84, 7, v85
	s_movk_i32 s44, 0x2200
	v_mul_lo_u32 v86, v84, s44
	v_add_u32_e32 v15, v86, v85
	v_lshlrev_b32_e32 v84, 10, v80
	v_lshl_add_u32 v248, v81, 4, v84
	v_add_u32_e32 v249, 0x4000, v248
	v_lshlrev_b32_e32 v84, 11, v80
	v_lshl_add_u32 v200, v81, 3, v84
	v_add_u32_e32 v201, 0x8000, v200
	global_load_dwordx4 v[16:19], v248, s[50:51]
	global_load_dwordx4 v[20:23], v248, s[50:51] offset:64
	global_load_dwordx4 v[24:27], v249, s[50:51]
	global_load_dwordx4 v[28:31], v249, s[50:51] offset:64
	v_readlane_b32 s46, v254, 0
	v_readlane_b32 s47, v254, 1
	s_sub_u32 s46, s46, 0xd8
	s_subb_u32 s47, s47, 0
	s_load_dwordx2 s[40:41], s[46:47], 0x58
	s_load_dwordx2 s[42:43], s[46:47], 0x60
	v_lshlrev_b32_e32 v84, 2, v1
	s_waitcnt lgkmcnt(0)
	global_load_dword v85, v84, s[40:41]
	global_load_dword v86, v84, s[42:43]
	s_waitcnt vmcnt(0) lgkmcnt(0)
; __device__ __forceinline__ void attn_unit(int b, int qb, int kvh, const bf16_t* __restrict__ QP, const bf16_t* __restrict__ KP, const bf16_t* __restrict__ VT, const float* sink, bf16_t* MIX, unsigned char* ldsb, int tid, int wave, int lane) {
;     ...
;     const float sk = sink[hq] * LOG2E;
; #pragma unroll
;     for (int qt = 0; qt < 2; ++qt) { mrun[qt] = sk; lrun[qt] = fq == 0 ? 1.0f : 0.0f;
; #pragma unroll
;         for (int dt = 0; dt < 4; ++dt) o[dt][qt] = (f32x4){0.f, 0.f, 0.f, 0.f}; }
;     const int first = qb == 0 ? 2 : (qb == 1 ? 1 : 0), lastw = (65 - qb) < 4 ? (65 - qb) : 4, nW = lastw - first + 1, nT = nW + 4;
;     ...
;     bf16_t* const lb = (bf16_t*)ldsb; const int lr = tid >> 3, lc = tid & 7;
;     u32x4 kreg = *(const u32x4*)(Kb + (size_t)(ATT_KS0(0) + lr) * 64 + lc * 8), vreg = *(const u32x4*)(Vb + (size_t)lr * KPL + ATT_KS0(0) + lc * 8);
;     __syncthreads();
;     *(u32x4*)(lb + lr * 72 + lc * 8) = kreg; *(u32x4*)(lb + 4608 + lr * 72 + lc * 8) = vreg;
;     __syncthreads();
;     for (int jt = 0; jt < nT; ++jt) {
;         const int ks0 = ATT_KS0(jt); const bool needmask = (jt < nW) && !((ks0 + 63 - q0 <= 128) && (q0 + 31 - ks0 <= 128)); const bf16_t* Kc = lb + (jt & 1) * 9216; const bf16_t* Vc = Kc + 4608;
;         if (jt + 1 < nT) { const int kn0 = ATT_KS0(jt + 1); kreg = *(const u32x4*)(Kb + (size_t)(kn0 + lr) * 64 + lc * 8); vreg = *(const u32x4*)(Vb + (size_t)lr * KPL + kn0 + lc * 8); }
;     ...
;         for (int qt = 0; qt < 2; ++qt) { const int qpos = q0 + qt * 16 + fr; float mx = -3.0e38f;
; #pragma unroll
;             for (int kt = 0; kt < 4; ++kt)
; #pragma unroll
;                 for (int j = 0; j < 4; ++j) { float v = s[kt][qt][j]; if (needmask) { const int dd = ks0 + kt * 16 + 4 * fq + j - qpos; if (dd > 128 || dd < -128) v = -1.0e30f; s[kt][qt][j] = v; } mx = fmaxf(mx, v); }
	v_max_f32_e64 v85, |v85|, |v85|
	v_max_f32_e64 v86, |v86|, |v86|
	s_nop 1
	v_max_f32_dpp v85, v85, v85 quad_perm:[1,0,3,2] row_mask:0xf bank_mask:0xf
	s_nop 1
	v_max_f32_dpp v85, v85, v85 quad_perm:[2,3,0,1] row_mask:0xf bank_mask:0xf
	s_nop 1
	v_max_f32_dpp v85, v85, v85 row_half_mirror row_mask:0xf bank_mask:0xf
	s_nop 1
	v_max_f32_dpp v85, v85, v85 row_mirror row_mask:0xf bank_mask:0xf
	s_nop 1
	v_mov_b32_e32 v87, v85
	s_nop 1
	v_permlane16_swap_b32_e32 v85, v87
	s_nop 0
	v_max_f32_e32 v85, v85, v87
	v_mov_b32_e32 v87, v85
	s_nop 1
	v_permlane32_swap_b32_e32 v85, v87
	s_nop 0
	v_max_f32_e32 v85, v85, v87
	s_nop 1
	v_max_f32_dpp v86, v86, v86 quad_perm:[1,0,3,2] row_mask:0xf bank_mask:0xf
	s_nop 1
	v_max_f32_dpp v86, v86, v86 quad_perm:[2,3,0,1] row_mask:0xf bank_mask:0xf
	s_nop 1
	v_max_f32_dpp v86, v86, v86 row_half_mirror row_mask:0xf bank_mask:0xf
	s_nop 1
	v_max_f32_dpp v86, v86, v86 row_mirror row_mask:0xf bank_mask:0xf
	s_nop 1
	v_mov_b32_e32 v87, v86
	s_nop 1
	v_permlane16_swap_b32_e32 v86, v87
	s_nop 0
	v_max_f32_e32 v86, v86, v87
	v_mov_b32_e32 v87, v86
	s_nop 1
	v_permlane32_swap_b32_e32 v86, v87
	s_nop 0
	v_max_f32_e32 v86, v86, v87
	v_mul_f32_e32 v85, v85, v86
	v_mov_b32_e32 v86, 0.5
	v_fmamk_f32 v85, v85, 0x413c5bb7, v86
	v_mov_b32_e32 v86, 0x3fb8aa3b
	v_mul_f32_e32 v86, s45, v86
	v_max_f32_e32 v85, v85, v86
	v_sub_f32_e32 v251, 0, v85
	v_sub_f32_e32 v86, v86, v85
	v_exp_f32_e32 v86, v86
	v_mov_b32_e32 v253, 0
	v_mov_b32_e32 v252, 0xf149f2ca
	v_cmp_gt_u32_e64 s[4:5], 16, v1
	s_nop 1
	v_cndmask_b32_e64 v250, 0, v86, s[4:5]
	v_mov_b32_e32 v196, v251
	v_mov_b32_e32 v197, v251
	v_mov_b32_e32 v198, v251
	v_mov_b32_e32 v199, v251
	v_lshlrev_b32_e32 v84, 2, v81
	v_sub_u32_e32 v84, v84, v80
	s_and_b32 s44, s12, 1
	s_lshl_b32 s44, s44, 5
	v_subrev_u32_e32 v84, s44, v84
	v_add_u32_e32 v85, -16, v84
	v_cmp_le_i32_e64 s[4:5], 0, v85
	v_cmp_ge_i32_e64 s[6:7], 0, v85
	s_nop 1
	v_cndmask_b32_e64 v208, v252, v251, s[4:5]
	v_cndmask_b32_e64 v228, v252, v251, s[6:7]
	v_add_u32_e32 v85, -15, v84
	v_cmp_le_i32_e64 s[4:5], 0, v85
	v_cmp_ge_i32_e64 s[6:7], 0, v85
	s_nop 1
	v_cndmask_b32_e64 v209, v252, v251, s[4:5]
	v_cndmask_b32_e64 v229, v252, v251, s[6:7]
	v_add_u32_e32 v85, -14, v84
	v_cmp_le_i32_e64 s[4:5], 0, v85
	v_cmp_ge_i32_e64 s[6:7], 0, v85
	s_nop 1
	v_cndmask_b32_e64 v210, v252, v251, s[4:5]
	v_cndmask_b32_e64 v230, v252, v251, s[6:7]
	v_add_u32_e32 v85, -13, v84
	v_cmp_le_i32_e64 s[4:5], 0, v85
	v_cmp_ge_i32_e64 s[6:7], 0, v85
	s_nop 1
	v_cndmask_b32_e64 v211, v252, v251, s[4:5]
	v_cndmask_b32_e64 v231, v252, v251, s[6:7]
	v_add_u32_e32 v85, 0, v84
	v_cmp_le_i32_e64 s[4:5], 0, v85
	v_cmp_ge_i32_e64 s[6:7], 0, v85
	s_nop 1
	v_cndmask_b32_e64 v212, v252, v251, s[4:5]
	v_cndmask_b32_e64 v232, v252, v251, s[6:7]
	v_add_u32_e32 v85, 1, v84
	v_cmp_le_i32_e64 s[4:5], 0, v85
	v_cmp_ge_i32_e64 s[6:7], 0, v85
	s_nop 1
	v_cndmask_b32_e64 v213, v252, v251, s[4:5]
	v_cndmask_b32_e64 v233, v252, v251, s[6:7]
	v_add_u32_e32 v85, 2, v84
	v_cmp_le_i32_e64 s[4:5], 0, v85
	v_cmp_ge_i32_e64 s[6:7], 0, v85
	s_nop 1
	v_cndmask_b32_e64 v214, v252, v251, s[4:5]
	v_cndmask_b32_e64 v234, v252, v251, s[6:7]
	v_add_u32_e32 v85, 3, v84
	v_cmp_le_i32_e64 s[4:5], 0, v85
	v_cmp_ge_i32_e64 s[6:7], 0, v85
	s_nop 1
	v_cndmask_b32_e64 v215, v252, v251, s[4:5]
	v_cndmask_b32_e64 v235, v252, v251, s[6:7]
	v_add_u32_e32 v85, 16, v84
	v_cmp_le_i32_e64 s[4:5], 0, v85
	v_cmp_ge_i32_e64 s[6:7], 0, v85
	s_nop 1
	v_cndmask_b32_e64 v216, v252, v251, s[4:5]
	v_cndmask_b32_e64 v236, v252, v251, s[6:7]
	v_add_u32_e32 v85, 17, v84
	v_cmp_le_i32_e64 s[4:5], 0, v85
	v_cmp_ge_i32_e64 s[6:7], 0, v85
	s_nop 1
	v_cndmask_b32_e64 v217, v252, v251, s[4:5]
	v_cndmask_b32_e64 v237, v252, v251, s[6:7]
	v_add_u32_e32 v85, 18, v84
	v_cmp_le_i32_e64 s[4:5], 0, v85
	v_cmp_ge_i32_e64 s[6:7], 0, v85
	s_nop 1
	v_cndmask_b32_e64 v218, v252, v251, s[4:5]
	v_cndmask_b32_e64 v238, v252, v251, s[6:7]
	v_add_u32_e32 v85, 19, v84
	v_cmp_le_i32_e64 s[4:5], 0, v85
	v_cmp_ge_i32_e64 s[6:7], 0, v85
	s_nop 1
	v_cndmask_b32_e64 v219, v252, v251, s[4:5]
	v_cndmask_b32_e64 v239, v252, v251, s[6:7]
	v_add_u32_e32 v85, 32, v84
	v_cmp_le_i32_e64 s[4:5], 0, v85
	v_cmp_ge_i32_e64 s[6:7], 0, v85
	s_nop 1
	v_cndmask_b32_e64 v220, v252, v251, s[4:5]
	v_cndmask_b32_e64 v240, v252, v251, s[6:7]
	v_add_u32_e32 v85, 33, v84
	v_cmp_le_i32_e64 s[4:5], 0, v85
	v_cmp_ge_i32_e64 s[6:7], 0, v85
	s_nop 1
	v_cndmask_b32_e64 v221, v252, v251, s[4:5]
	v_cndmask_b32_e64 v241, v252, v251, s[6:7]
	v_add_u32_e32 v85, 34, v84
	v_cmp_le_i32_e64 s[4:5], 0, v85
	v_cmp_ge_i32_e64 s[6:7], 0, v85
	s_nop 1
	v_cndmask_b32_e64 v222, v252, v251, s[4:5]
	v_cndmask_b32_e64 v242, v252, v251, s[6:7]
	v_add_u32_e32 v85, 35, v84
	v_cmp_le_i32_e64 s[4:5], 0, v85
	v_cmp_ge_i32_e64 s[6:7], 0, v85
	s_nop 1
	v_cndmask_b32_e64 v223, v252, v251, s[4:5]
	v_cndmask_b32_e64 v243, v252, v251, s[6:7]
	v_add_u32_e32 v85, 48, v84
	v_cmp_le_i32_e64 s[4:5], 0, v85
	v_cmp_ge_i32_e64 s[6:7], 0, v85
	s_nop 1
	v_cndmask_b32_e64 v224, v252, v251, s[4:5]
	v_cndmask_b32_e64 v244, v252, v251, s[6:7]
	v_add_u32_e32 v85, 49, v84
	v_cmp_le_i32_e64 s[4:5], 0, v85
	v_cmp_ge_i32_e64 s[6:7], 0, v85
	s_nop 1
	v_cndmask_b32_e64 v225, v252, v251, s[4:5]
	v_cndmask_b32_e64 v245, v252, v251, s[6:7]
	v_add_u32_e32 v85, 50, v84
	v_cmp_le_i32_e64 s[4:5], 0, v85
	v_cmp_ge_i32_e64 s[6:7], 0, v85
	s_nop 1
	v_cndmask_b32_e64 v226, v252, v251, s[4:5]
	v_cndmask_b32_e64 v246, v252, v251, s[6:7]
	v_add_u32_e32 v85, 51, v84
	v_cmp_le_i32_e64 s[4:5], 0, v85
	v_cmp_ge_i32_e64 s[6:7], 0, v85
	s_nop 1
	v_cndmask_b32_e64 v227, v252, v251, s[4:5]
	v_cndmask_b32_e64 v247, v252, v251, s[6:7]
	s_mov_b32 s27, 0
	s_mov_b32 s30, 0
	s_mov_b32 s31, 0
	s_mov_b32 s28, 0
	s_mov_b32 s29, 0
	s_mov_b32 s35, 0
	s_cmp_lt_u32 s28, s24
	s_cbranch_scc0 .Lat_ctx_1
	s_add_u32 s44, s13, s21
	s_add_u32 s44, s44, s28
	s_lshl_b32 s44, s44, 6
	s_sub_u32 s44, s44, 0x80
	s_branch .Lat_ks_2
.Lat_ctx_1:
	s_sub_u32 s44, s28, s24
	s_lshl_b32 s44, s44, 6
	s_add_u32 s44, s44, 0x1000
.Lat_ks_2:
	s_mul_i32 s45, s29, 0x220000
	s_lshl_b32 s46, s44, 7
	s_add_u32 s46, s46, s45
	s_add_u32 s40, s8, s46
	s_addc_u32 s41, s9, 0
	s_lshl_b32 s46, s44, 1
	s_add_u32 s46, s46, s45
	s_add_u32 s42, s10, s46
	s_addc_u32 s43, s11, 0
	s_and_b32 s47, s35, 3
	s_lshl_b32 s47, s47, 14
	s_add_u32 s47, s47, s34
	s_mov_b32 m0, s47
	s_add_u32 s47, s47, 0x2000
	global_load_lds_dwordx4 v14, s[40:41]
	s_mov_b32 m0, s47
	s_add_u32 s35, s35, 1
	global_load_lds_dwordx4 v15, s[42:43]
	s_add_u32 s28, s28, 1
	s_cmp_lt_u32 s28, s25
	s_cbranch_scc1 .Lat_adv_3
	s_cmp_lt_u32 s29, 3
	s_cbranch_scc0 .Lat_clamp_4
	s_add_u32 s29, s29, 1
	s_mov_b32 s28, 0
	s_branch .Lat_adv_3
.Lat_clamp_4:
	s_sub_u32 s28, s25, 1
.Lat_adv_3:
	s_cmp_lt_u32 s28, s24
	s_cbranch_scc0 .Lat_ctx_5
	s_add_u32 s44, s13, s21
	s_add_u32 s44, s44, s28
	s_lshl_b32 s44, s44, 6
	s_sub_u32 s44, s44, 0x80
	s_branch .Lat_ks_6

; __device__ __forceinline__ void attn_unit(int b, int qb, int kvh, const bf16_t* __restrict__ QP, const bf16_t* __restrict__ KP, const bf16_t* __restrict__ VT, const float* sink, bf16_t* MIX, unsigned char* ldsb, int tid, int wave, int lane) {
;     ...
;     for (int jt = 0; jt < nT; ++jt) {
;         const int ks0 = ATT_KS0(jt); const bool needmask = (jt < nW) && !((ks0 + 63 - q0 <= 128) && (q0 + 31 - ks0 <= 128)); const bf16_t* Kc = lb + (jt & 1) * 9216; const bf16_t* Vc = Kc + 4608;
;         if (jt + 1 < nT) { const int kn0 = ATT_KS0(jt + 1); kreg = *(const u32x4*)(Kb + (size_t)(kn0 + lr) * 64 + lc * 8); vreg = *(const u32x4*)(Vb + (size_t)lr * KPL + kn0 + lc * 8); }
.Lat_adv_11:
.Lat_loop:
	s_waitcnt vmcnt(4)
	s_barrier
	s_cmp_lt_u32 s28, s24
	s_cbranch_scc0 .Lat_ctx_13
	s_add_u32 s44, s13, s21
	s_add_u32 s44, s44, s28
	s_lshl_b32 s44, s44, 6
	s_sub_u32 s44, s44, 0x80
	s_branch .Lat_ks_14

; __device__ __forceinline__ void attn_unit(int b, int qb, int kvh, const bf16_t* __restrict__ QP, const bf16_t* __restrict__ KP, const bf16_t* __restrict__ VT, const float* sink, bf16_t* MIX, unsigned char* ldsb, int tid, int wave, int lane) {
;     ...
;     for (int jt = 0; jt < nT; ++jt) {
;         const int ks0 = ATT_KS0(jt); const bool needmask = (jt < nW) && !((ks0 + 63 - q0 <= 128) && (q0 + 31 - ks0 <= 128)); const bf16_t* Kc = lb + (jt & 1) * 9216; const bf16_t* Vc = Kc + 4608;
;         if (jt + 1 < nT) { const int kn0 = ATT_KS0(jt + 1); kreg = *(const u32x4*)(Kb + (size_t)(kn0 + lr) * 64 + lc * 8); vreg = *(const u32x4*)(Vb + (size_t)lr * KPL + kn0 + lc * 8); }
;         bf16x8 kf[4][2];
; #pragma unroll
;         for (int kt = 0; kt < 4; ++kt)
; #pragma unroll
;             for (int ks = 0; ks < 2; ++ks) kf[kt][ks] = *(const bf16x8*)(Kc + (kt * 16 + fr) * 72 + ks * 32 + fq * 8);
;         u32x2 vr[4][2][2];
; #pragma unroll
;         for (int dt = 0; dt < 4; ++dt)
; #pragma unroll
;             for (int kk = 0; kk < 2; ++kk) { const bf16_t* vp = Vc + (dt * 16 + fr) * 72 + kk * 32 + 4 * fq; vr[dt][kk][0] = *(const u32x2*)vp; vr[dt][kk][1] = *(const u32x2*)(vp + 16); }
;         f32x4 s[4][2];
; #pragma unroll
;         for (int kt = 0; kt < 4; ++kt)
; #pragma unroll
;             for (int qt = 0; qt < 2; ++qt) { f32x4 a = (f32x4){0.f, 0.f, 0.f, 0.f};
; #pragma unroll
;                 for (int ks = 0; ks < 2; ++ks) a = __builtin_amdgcn_mfma_f32_16x16x32_bf16(kf[kt][ks], qf[qt][ks], a, 0, 0, 0);
;                 s[kt][qt] = a; }
.Lat_adv_15:
	s_and_b32 s33, s27, 3
	s_lshl_b32 s33, s33, 14
	v_add_u32_e32 v8, s33, v2
	v_add_u32_e32 v9, s33, v3
	v_add_u32_e32 v10, s33, v4
	v_add_u32_e32 v11, s33, v5
	v_add_u32_e32 v12, s33, v6
	v_add_u32_e32 v13, s33, v7
	ds_read_b128 v[112:115], v8
	ds_read_b128 v[116:119], v9
	ds_read_b128 v[120:123], v8 offset:2048
	ds_read_b128 v[124:127], v9 offset:2048
	ds_read_b128 v[128:131], v8 offset:4096
	ds_read_b128 v[132:135], v9 offset:4096
	ds_read_b128 v[136:139], v8 offset:6144
	ds_read_b128 v[140:143], v9 offset:6144
	ds_read_b64 v[144:145], v10 offset:8192
	ds_read_b64 v[146:147], v11 offset:8192
	ds_read_b64 v[152:153], v10 offset:10240
	ds_read_b64 v[154:155], v11 offset:10240
	ds_read_b64 v[160:161], v10 offset:12288
	ds_read_b64 v[162:163], v11 offset:12288
	ds_read_b64 v[168:169], v10 offset:14336
	s_cmp_lg_u32 s30, 0
	s_cbranch_scc1 .Lat_nofirst
	v_mov_b32_e32 v48, 0
	v_mov_b32_e32 v49, 0
	v_mov_b32_e32 v50, 0
	v_mov_b32_e32 v51, 0
	v_mov_b32_e32 v52, 0
	v_mov_b32_e32 v53, 0
	v_mov_b32_e32 v54, 0
	v_mov_b32_e32 v55, 0
	v_mov_b32_e32 v56, 0
	v_mov_b32_e32 v57, 0
	v_mov_b32_e32 v58, 0
	v_mov_b32_e32 v59, 0
	v_mov_b32_e32 v60, 0
	v_mov_b32_e32 v61, 0
	v_mov_b32_e32 v62, 0
	v_mov_b32_e32 v63, 0
	v_mov_b32_e32 v64, 0
	v_mov_b32_e32 v65, 0
	v_mov_b32_e32 v66, 0
	v_mov_b32_e32 v67, 0
	v_mov_b32_e32 v68, 0
	v_mov_b32_e32 v69, 0
	v_mov_b32_e32 v70, 0
	v_mov_b32_e32 v71, 0
	v_mov_b32_e32 v72, 0
	v_mov_b32_e32 v73, 0
	v_mov_b32_e32 v74, 0
	v_mov_b32_e32 v75, 0
	v_mov_b32_e32 v76, 0
	v_mov_b32_e32 v77, 0
	v_mov_b32_e32 v78, 0
	v_mov_b32_e32 v79, 0
	v_mov_b32_e32 v192, v250
	v_mov_b32_e32 v193, 0
	v_mov_b32_e32 v194, v250
	v_mov_b32_e32 v195, 0
	s_cmp_lt_u32 s31, 3
	s_cbranch_scc0 .Lat_nofirst
	s_add_u32 s0, s31, 1
	s_lshl_b32 s0, s0, 23
	s_add_u32 s36, s50, s0
	s_addc_u32 s37, s51, 0
	global_load_dwordx4 v[32:35], v248, s[36:37]
	global_load_dwordx4 v[36:39], v248, s[36:37] offset:64
	global_load_dwordx4 v[40:43], v249, s[36:37]
	global_load_dwordx4 v[44:47], v249, s[36:37] offset:64
.Lat_nofirst:
	s_cmp_lt_u32 s30, s24
	s_cbranch_scc0 .Lat_qk_plain
	s_add_u32 s0, s21, s30
	s_cmp_eq_u32 s0, 0
	s_cbranch_scc1 .Lat_qk_A
	s_cmp_eq_u32 s0, 4
	s_cbranch_scc1 .Lat_qk_B
.Lat_qk_plain:
	s_waitcnt lgkmcnt(7)
	v_mfma_f32_16x16x32_bf16 v[80:83], v[112:115], v[16:19], v[196:199]
	v_mfma_f32_16x16x32_bf16 v[80:83], v[116:119], v[20:23], v[80:83]
	v_mfma_f32_16x16x32_bf16 v[84:87], v[112:115], v[24:27], v[196:199]
	v_mfma_f32_16x16x32_bf16 v[84:87], v[116:119], v[28:31], v[84:87]
	v_mfma_f32_16x16x32_bf16 v[88:91], v[120:123], v[16:19], v[196:199]
	v_mfma_f32_16x16x32_bf16 v[88:91], v[124:127], v[20:23], v[88:91]
	v_mfma_f32_16x16x32_bf16 v[92:95], v[120:123], v[24:27], v[196:199]
	v_mfma_f32_16x16x32_bf16 v[92:95], v[124:127], v[28:31], v[92:95]
	v_mfma_f32_16x16x32_bf16 v[96:99], v[128:131], v[16:19], v[196:199]
	v_mfma_f32_16x16x32_bf16 v[96:99], v[132:135], v[20:23], v[96:99]
	v_mfma_f32_16x16x32_bf16 v[100:103], v[128:131], v[24:27], v[196:199]
	v_mfma_f32_16x16x32_bf16 v[100:103], v[132:135], v[28:31], v[100:103]
	v_mfma_f32_16x16x32_bf16 v[104:107], v[136:139], v[16:19], v[196:199]
	v_mfma_f32_16x16x32_bf16 v[104:107], v[140:143], v[20:23], v[104:107]
	v_mfma_f32_16x16x32_bf16 v[108:111], v[136:139], v[24:27], v[196:199]
	v_mfma_f32_16x16x32_bf16 v[108:111], v[140:143], v[28:31], v[108:111]
	s_branch .Lat_qk_done
.Lat_qk_A:
	s_waitcnt lgkmcnt(7)
	v_mfma_f32_16x16x32_bf16 v[80:83], v[112:115], v[16:19], v[212:215]
	v_mfma_f32_16x16x32_bf16 v[80:83], v[116:119], v[20:23], v[80:83]
	v_mfma_f32_16x16x32_bf16 v[84:87], v[112:115], v[24:27], v[208:211]
	v_mfma_f32_16x16x32_bf16 v[84:87], v[116:119], v[28:31], v[84:87]
	v_mfma_f32_16x16x32_bf16 v[88:91], v[120:123], v[16:19], v[216:219]
	v_mfma_f32_16x16x32_bf16 v[88:91], v[124:127], v[20:23], v[88:91]
	v_mfma_f32_16x16x32_bf16 v[92:95], v[120:123], v[24:27], v[212:215]
	v_mfma_f32_16x16x32_bf16 v[92:95], v[124:127], v[28:31], v[92:95]
	v_mfma_f32_16x16x32_bf16 v[96:99], v[128:131], v[16:19], v[220:223]
	v_mfma_f32_16x16x32_bf16 v[96:99], v[132:135], v[20:23], v[96:99]
	v_mfma_f32_16x16x32_bf16 v[100:103], v[128:131], v[24:27], v[216:219]
	v_mfma_f32_16x16x32_bf16 v[100:103], v[132:135], v[28:31], v[100:103]
	v_mfma_f32_16x16x32_bf16 v[104:107], v[136:139], v[16:19], v[224:227]
	v_mfma_f32_16x16x32_bf16 v[104:107], v[140:143], v[20:23], v[104:107]
	v_mfma_f32_16x16x32_bf16 v[108:111], v[136:139], v[24:27], v[220:223]
	v_mfma_f32_16x16x32_bf16 v[108:111], v[140:143], v[28:31], v[108:111]
	s_branch .Lat_qk_done
.Lat_qk_B:
	s_waitcnt lgkmcnt(7)
	v_mfma_f32_16x16x32_bf16 v[80:83], v[112:115], v[16:19], v[232:235]
	v_mfma_f32_16x16x32_bf16 v[80:83], v[116:119], v[20:23], v[80:83]
	v_mfma_f32_16x16x32_bf16 v[84:87], v[112:115], v[24:27], v[228:231]
	v_mfma_f32_16x16x32_bf16 v[84:87], v[116:119], v[28:31], v[84:87]
	v_mfma_f32_16x16x32_bf16 v[88:91], v[120:123], v[16:19], v[236:239]
	v_mfma_f32_16x16x32_bf16 v[88:91], v[124:127], v[20:23], v[88:91]
	v_mfma_f32_16x16x32_bf16 v[92:95], v[120:123], v[24:27], v[232:235]
	v_mfma_f32_16x16x32_bf16 v[92:95], v[124:127], v[28:31], v[92:95]
	v_mfma_f32_16x16x32_bf16 v[96:99], v[128:131], v[16:19], v[240:243]
	v_mfma_f32_16x16x32_bf16 v[96:99], v[132:135], v[20:23], v[96:99]
	v_mfma_f32_16x16x32_bf16 v[100:103], v[128:131], v[24:27], v[236:239]
	v_mfma_f32_16x16x32_bf16 v[100:103], v[132:135], v[28:31], v[100:103]
	v_mfma_f32_16x16x32_bf16 v[104:107], v[136:139], v[16:19], v[244:247]
	v_mfma_f32_16x16x32_bf16 v[104:107], v[140:143], v[20:23], v[104:107]
	v_mfma_f32_16x16x32_bf16 v[108:111], v[136:139], v[24:27], v[240:243]
	v_mfma_f32_16x16x32_bf16 v[108:111], v[140:143], v[28:31], v[108:111]
; __device__ __forceinline__ void attn_unit(int b, int qb, int kvh, const bf16_t* __restrict__ QP, const bf16_t* __restrict__ KP, const bf16_t* __restrict__ VT, const float* sink, bf16_t* MIX, unsigned char* ldsb, int tid, int wave, int lane) {
;     ...
;         for (int qt = 0; qt < 2; ++qt) { const int qpos = q0 + qt * 16 + fr; float mx = -3.0e38f;
; #pragma unroll
;             for (int kt = 0; kt < 4; ++kt)
; #pragma unroll
;                 for (int j = 0; j < 4; ++j) { float v = s[kt][qt][j]; if (needmask) { const int dd = ks0 + kt * 16 + 4 * fq + j - qpos; if (dd > 128 || dd < -128) v = -1.0e30f; s[kt][qt][j] = v; } mx = fmaxf(mx, v); }
;             mx = fmaxf(mx, __shfl_xor(mx, 16)); mx = fmaxf(mx, __shfl_xor(mx, 32));
;             const float mnew = fmaxf(mrun[qt], mx), alpha = __builtin_amdgcn_exp2f(mrun[qt] - mnew); mrun[qt] = mnew; float ls = 0.f;
; #pragma unroll
;             for (int kt = 0; kt < 4; ++kt)
; #pragma unroll
;                 for (int j = 0; j < 4; ++j) { const float p = __builtin_amdgcn_exp2f(s[kt][qt][j] - mnew); s[kt][qt][j] = p; ls += p; }
;             lrun[qt] = lrun[qt] * alpha + ls;
; #pragma unroll
;             for (int dt = 0; dt < 4; ++dt) o[dt][qt] *= alpha;
; #pragma unroll
;             for (int kk = 0; kk < 2; ++kk) { u32x4 w; w.x = cvt_pk_bf16(s[2 * kk][qt][0], s[2 * kk][qt][1]); w.y = cvt_pk_bf16(s[2 * kk][qt][2], s[2 * kk][qt][3]);
;                 w.z = cvt_pk_bf16(s[2 * kk + 1][qt][0], s[2 * kk + 1][qt][1]); w.w = cvt_pk_bf16(s[2 * kk + 1][qt][2], s[2 * kk + 1][qt][3]); pf[qt][kk] = __builtin_bit_cast(bf16x8, w); } }
; #pragma unroll
;         for (int dt = 0; dt < 4; ++dt)
; #pragma unroll
;             for (int kk = 0; kk < 2; ++kk) { u32x4 w; w.x = vr[dt][kk][0].x; w.y = vr[dt][kk][0].y; w.z = vr[dt][kk][1].x; w.w = vr[dt][kk][1].y; const bf16x8 vf = __builtin_bit_cast(bf16x8, w);
; #pragma unroll
;                 for (int qt = 0; qt < 2; ++qt) o[dt][qt] = __builtin_amdgcn_mfma_f32_16x16x32_bf16(vf, pf[qt][kk], o[dt][qt], 0, 0, 0); }
;         if (jt + 1 < nT) { bf16_t* Kn = lb + ((jt + 1) & 1) * 9216; *(u32x4*)(Kn + lr * 72 + lc * 8) = kreg; *(u32x4*)(Kn + 4608 + lr * 72 + lc * 8) = vreg; }
;         __syncthreads();
;     }
;     ...
; #pragma unroll
;     for (int qt = 0; qt < 2; ++qt) { float l = lrun[qt]; l += __shfl_xor(l, 16); l += __shfl_xor(l, 32); const float inv = 1.0f / l;
.Lat_qk_done:
	ds_read_b64 v[170:171], v11 offset:14336
	ds_read_b64 v[148:149], v12 offset:8192
	ds_read_b64 v[150:151], v13 offset:8192
	ds_read_b64 v[156:157], v12 offset:10240
	ds_read_b64 v[158:159], v13 offset:10240
	ds_read_b64 v[164:165], v12 offset:12288
	ds_read_b64 v[166:167], v13 offset:12288
	ds_read_b64 v[172:173], v12 offset:14336
	ds_read_b64 v[174:175], v13 offset:14336
	s_nop 4
	v_exp_f32_e32 v80, v80
	v_exp_f32_e32 v81, v81
	v_exp_f32_e32 v82, v82
	v_exp_f32_e32 v83, v83
	v_pk_add_f32 v[192:193], v[192:193], v[80:81]
	v_pk_add_f32 v[192:193], v[192:193], v[82:83]
	v_cvt_pk_bf16_f32 v176, v80, v81
	v_cvt_pk_bf16_f32 v177, v82, v83
	v_exp_f32_e32 v84, v84
	v_exp_f32_e32 v85, v85
	v_exp_f32_e32 v86, v86
	v_exp_f32_e32 v87, v87
	v_pk_add_f32 v[194:195], v[194:195], v[84:85]
	v_pk_add_f32 v[194:195], v[194:195], v[86:87]
	v_cvt_pk_bf16_f32 v184, v84, v85
	v_cvt_pk_bf16_f32 v185, v86, v87
	v_exp_f32_e32 v88, v88
	v_exp_f32_e32 v89, v89
	v_exp_f32_e32 v90, v90
	v_exp_f32_e32 v91, v91
	v_pk_add_f32 v[192:193], v[192:193], v[88:89]
	v_pk_add_f32 v[192:193], v[192:193], v[90:91]
	v_cvt_pk_bf16_f32 v178, v88, v89
	v_cvt_pk_bf16_f32 v179, v90, v91
	v_exp_f32_e32 v92, v92
	v_exp_f32_e32 v93, v93
	v_exp_f32_e32 v94, v94
	v_exp_f32_e32 v95, v95
	v_pk_add_f32 v[194:195], v[194:195], v[92:93]
	v_pk_add_f32 v[194:195], v[194:195], v[94:95]
	v_cvt_pk_bf16_f32 v186, v92, v93
	v_cvt_pk_bf16_f32 v187, v94, v95
	s_waitcnt lgkmcnt(8)
	v_exp_f32_e32 v96, v96
	v_exp_f32_e32 v97, v97
	v_exp_f32_e32 v98, v98
	v_exp_f32_e32 v99, v99
	v_pk_add_f32 v[192:193], v[192:193], v[96:97]
	v_pk_add_f32 v[192:193], v[192:193], v[98:99]
	v_cvt_pk_bf16_f32 v180, v96, v97
	v_cvt_pk_bf16_f32 v181, v98, v99
	v_mfma_f32_16x16x32_bf16 v[48:51], v[144:147], v[176:179], v[48:51]
	v_mfma_f32_16x16x32_bf16 v[52:55], v[144:147], v[184:187], v[52:55]
	v_exp_f32_e32 v100, v100
	v_exp_f32_e32 v101, v101
	v_exp_f32_e32 v102, v102
	v_exp_f32_e32 v103, v103
	v_pk_add_f32 v[194:195], v[194:195], v[100:101]
	v_pk_add_f32 v[194:195], v[194:195], v[102:103]
	v_cvt_pk_bf16_f32 v188, v100, v101
	v_cvt_pk_bf16_f32 v189, v102, v103
	v_mfma_f32_16x16x32_bf16 v[56:59], v[152:155], v[176:179], v[56:59]
	v_mfma_f32_16x16x32_bf16 v[60:63], v[152:155], v[184:187], v[60:63]
	v_exp_f32_e32 v104, v104
	v_exp_f32_e32 v105, v105
	v_exp_f32_e32 v106, v106
	v_exp_f32_e32 v107, v107
	v_pk_add_f32 v[192:193], v[192:193], v[104:105]
	v_pk_add_f32 v[192:193], v[192:193], v[106:107]
	v_cvt_pk_bf16_f32 v182, v104, v105
	v_cvt_pk_bf16_f32 v183, v106, v107
	v_mfma_f32_16x16x32_bf16 v[64:67], v[160:163], v[176:179], v[64:67]
	v_mfma_f32_16x16x32_bf16 v[68:71], v[160:163], v[184:187], v[68:71]
	v_exp_f32_e32 v108, v108
	v_exp_f32_e32 v109, v109
	v_exp_f32_e32 v110, v110
	v_exp_f32_e32 v111, v111
	v_pk_add_f32 v[194:195], v[194:195], v[108:109]
	v_pk_add_f32 v[194:195], v[194:195], v[110:111]
	v_cvt_pk_bf16_f32 v190, v108, v109
	v_cvt_pk_bf16_f32 v191, v110, v111
	v_mfma_f32_16x16x32_bf16 v[72:75], v[168:171], v[176:179], v[72:75]
	v_mfma_f32_16x16x32_bf16 v[76:79], v[168:171], v[184:187], v[76:79]
	s_waitcnt lgkmcnt(0)
	v_mfma_f32_16x16x32_bf16 v[48:51], v[148:151], v[180:183], v[48:51]
	v_mfma_f32_16x16x32_bf16 v[52:55], v[148:151], v[188:191], v[52:55]
	v_mfma_f32_16x16x32_bf16 v[56:59], v[156:159], v[180:183], v[56:59]
	v_mfma_f32_16x16x32_bf16 v[60:63], v[156:159], v[188:191], v[60:63]
	v_mfma_f32_16x16x32_bf16 v[64:67], v[164:167], v[180:183], v[64:67]
	v_mfma_f32_16x16x32_bf16 v[68:71], v[164:167], v[188:191], v[68:71]
	v_mfma_f32_16x16x32_bf16 v[72:75], v[172:175], v[180:183], v[72:75]
	v_mfma_f32_16x16x32_bf16 v[76:79], v[172:175], v[188:191], v[76:79]
	s_add_u32 s27, s27, 1
	s_add_u32 s30, s30, 1
	s_cmp_lt_u32 s30, s25
	s_cbranch_scc1 .Lat_cont
	s_lshl_b32 s0, s31, 24
	s_add_u32 s38, s52, s0
	s_addc_u32 s39, s53, 0
	s_nop 7
	v_add_f32_e32 v202, v192, v193
	v_add_f32_e32 v204, v194, v195
	v_mov_b32_e32 v203, v202
	v_mov_b32_e32 v205, v204
	s_nop 1
	v_permlane16_swap_b32_e32 v202, v203
	v_permlane16_swap_b32_e32 v204, v205
	s_nop 0
	v_add_f32_e32 v202, v202, v203
	v_add_f32_e32 v204, v204, v205
	v_mov_b32_e32 v203, v202
	v_mov_b32_e32 v205, v204
	s_nop 1
	v_permlane32_swap_b32_e32 v202, v203
	v_permlane32_swap_b32_e32 v204, v205
	s_nop 0
	v_add_f32_e32 v202, v202, v203
	v_add_f32_e32 v204, v204, v205
	v_rcp_f32_e32 v202, v202
	v_rcp_f32_e32 v204, v204
	s_nop 0
	v_pk_mul_f32 v[48:49], v[48:49], v[202:203] op_sel_hi:[1,0]
	v_pk_mul_f32 v[50:51], v[50:51], v[202:203] op_sel_hi:[1,0]
	v_cvt_pk_bf16_f32 v80, v48, v49
	v_cvt_pk_bf16_f32 v81, v50, v51
	global_store_dwordx2 v200, v[80:81], s[38:39]
	v_pk_mul_f32 v[52:53], v[52:53], v[204:205] op_sel_hi:[1,0]
	v_pk_mul_f32 v[54:55], v[54:55], v[204:205] op_sel_hi:[1,0]
	v_cvt_pk_bf16_f32 v82, v52, v53
	v_cvt_pk_bf16_f32 v83, v54, v55
	global_store_dwordx2 v201, v[82:83], s[38:39]
	v_pk_mul_f32 v[56:57], v[56:57], v[202:203] op_sel_hi:[1,0]
	v_pk_mul_f32 v[58:59], v[58:59], v[202:203] op_sel_hi:[1,0]
	v_cvt_pk_bf16_f32 v84, v56, v57
	v_cvt_pk_bf16_f32 v85, v58, v59
	global_store_dwordx2 v200, v[84:85], s[38:39] offset:32
	v_pk_mul_f32 v[60:61], v[60:61], v[204:205] op_sel_hi:[1,0]
	v_pk_mul_f32 v[62:63], v[62:63], v[204:205] op_sel_hi:[1,0]
	v_cvt_pk_bf16_f32 v86, v60, v61
	v_cvt_pk_bf16_f32 v87, v62, v63
	global_store_dwordx2 v201, v[86:87], s[38:39] offset:32
	v_pk_mul_f32 v[64:65], v[64:65], v[202:203] op_sel_hi:[1,0]
	v_pk_mul_f32 v[66:67], v[66:67], v[202:203] op_sel_hi:[1,0]
	v_cvt_pk_bf16_f32 v88, v64, v65
	v_cvt_pk_bf16_f32 v89, v66, v67
	global_store_dwordx2 v200, v[88:89], s[38:39] offset:64
	v_pk_mul_f32 v[68:69], v[68:69], v[204:205] op_sel_hi:[1,0]
	v_pk_mul_f32 v[70:71], v[70:71], v[204:205] op_sel_hi:[1,0]
	v_cvt_pk_bf16_f32 v90, v68, v69
	v_cvt_pk_bf16_f32 v91, v70, v71
	global_store_dwordx2 v201, v[90:91], s[38:39] offset:64
	v_pk_mul_f32 v[72:73], v[72:73], v[202:203] op_sel_hi:[1,0]
	v_pk_mul_f32 v[74:75], v[74:75], v[202:203] op_sel_hi:[1,0]
	v_cvt_pk_bf16_f32 v92, v72, v73
	v_cvt_pk_bf16_f32 v93, v74, v75
	global_store_dwordx2 v200, v[92:93], s[38:39] offset:96
	v_pk_mul_f32 v[76:77], v[76:77], v[204:205] op_sel_hi:[1,0]
	v_pk_mul_f32 v[78:79], v[78:79], v[204:205] op_sel_hi:[1,0]
	v_cvt_pk_bf16_f32 v94, v76, v77
	v_cvt_pk_bf16_f32 v95, v78, v79
	global_store_dwordx2 v201, v[94:95], s[38:39] offset:96
	v_mov_b32_e32 v16, v32
	v_mov_b32_e32 v17, v33
	v_mov_b32_e32 v18, v34
	v_mov_b32_e32 v19, v35
	v_mov_b32_e32 v20, v36
	v_mov_b32_e32 v21, v37
	v_mov_b32_e32 v22, v38
	v_mov_b32_e32 v23, v39
	v_mov_b32_e32 v24, v40
	v_mov_b32_e32 v25, v41
	v_mov_b32_e32 v26, v42
	v_mov_b32_e32 v27, v43
	v_mov_b32_e32 v28, v44
	v_mov_b32_e32 v29, v45
	v_mov_b32_e32 v30, v46
	v_mov_b32_e32 v31, v47
	s_mov_b32 s30, 0
	s_add_u32 s31, s31, 1
.Lat_cont:
	s_cmp_lt_u32 s27, s26
	s_cbranch_scc1 .Lat_loop
	s_add_u32 s6, s88, 0x1a600000
	s_addc_u32 s7, s89, 0
